# strategy 7.3: attention item's last fold writes its token rows as eight dwordx4 stores (v_permlane32_swap pairs the two 8-byte halves) instead of sixteen dwordx2 (on top of v023)
# speedup vs baseline: 1.0101x; 1.0101x over previous
; __device__ __forceinline__ unsigned pk2(float lo, float hi) { const bfx2 b = __builtin_convertvector((f32x2){lo, hi}, bfx2); return __builtin_bit_cast(unsigned, b); }
; __device__ __forceinline__ float bflo(unsigned w) { return __uint_as_float(w << 16); }
; __device__ __forceinline__ float bfhi(unsigned w) { return __uint_as_float(w & 0xffff0000u); }
; #define PKP(var) unsigned char* var; { int l_ = threadIdx.x; asm volatile("" : "+v"(l_)); var = ws + WS_PARK + (size_t)(item8 + (l_ >> 6)) * 8192 + (l_ & 63) * 16; }
; __device__ __forceinline__ void attn_item(const P& p, Frame& F, const bool is_s, const int b, const int g, const int c) {
;     ...
;     { const float lt = l + __shfl_xor(l, 32); const float sc = lt > 0.f ? NGt[(size_t)mrow * 32 + 2 * 8 + h] / lt : 0.f;
;       if (qvalid) { PKP(PK);
; #pragma unroll
;           for (int dt = 0; dt < 4; ++dt)
; #pragma unroll
;               for (int hf = 0; hf < 2; ++hf) { const u32x4 o4 = *(const u32x4*)(PK + (2 * dt + hf) * 1024);
; #pragma unroll
;                   for (int rr = 0; rr < 2; ++rr) { const int r4 = 2 * hf + rr; const int d0 = 32 * dt + 8 * r4 + 4 * half; const u32x2 o = rr ? (u32x2){o4.z, o4.w} : (u32x2){o4.x, o4.y};
;                       u32x2 w; w.x = pk2(bflo(o.x) + ot[dt][4 * r4 + 0] * sc, bfhi(o.x) + ot[dt][4 * r4 + 1] * sc); w.y = pk2(bflo(o.y) + ot[dt][4 * r4 + 2] * sc, bfhi(o.y) + ot[dt][4 * r4 + 3] * sc);
;                       *(u32x2*)(YN + (size_t)mrow * 1024 + h * 128 + d0) = w; } } } }
.LBB0_2141:
	s_waitcnt vmcnt(0)
	s_and_saveexec_b64 s[0:1], s[22:23]
	v_mov_b32_e32 v1, v0
	v_readlane_b32 s2, v252, 13
	v_ashrrev_i32_e32 v2, 6, v1
	v_lshlrev_b32_e32 v1, 4, v1
	v_add_u32_e32 v6, s2, v2
	v_ashrrev_i32_e32 v7, 31, v6
	v_readlane_b32 s2, v254, 49
	v_lshlrev_b64 v[6:7], 13, v[6:7]
	v_readlane_b32 s3, v254, 50
	v_and_b32_e32 v2, 0x3f0, v1
	s_nop 0
	v_lshl_add_u64 v[6:7], s[2:3], 0, v[6:7]
	v_lshl_add_u64 v[8:9], v[6:7], 0, v[2:3]
	s_movk_i32 s2, 0x1000
	s_nop 0
	v_add_co_u32_e32 v10, vcc, s2, v8
	s_nop 1
	v_addc_co_u32_e32 v11, vcc, 0, v9, vcc
	global_load_dword v16, v[202:203], off offset:64
	global_load_dwordx4 v[114:117], v[8:9], off
	global_load_dwordx4 v[118:121], v[8:9], off offset:1024
	global_load_dwordx4 v[122:125], v[8:9], off offset:2048
	global_load_dwordx4 v[126:129], v[8:9], off offset:3072
	global_load_dwordx4 v[130:133], v[10:11], off
	global_load_dwordx4 v[134:137], v[10:11], off offset:1024
	global_load_dwordx4 v[138:141], v[10:11], off offset:2048
	global_load_dwordx4 v[142:145], v[10:11], off offset:3072
	v_readlane_b32 s2, v252, 23
	v_readlane_b32 s3, v252, 24
	v_lshlrev_b32_e32 v2, 2, v229
	s_nop 1
	v_lshl_add_u64 v[6:7], s[2:3], 0, v[200:201]
	v_readlane_b32 s2, v252, 45
	s_nop 1
	s_lshl_b32 s44, s2, 1
	s_nop 0
	v_lshl_add_u64 v[6:7], v[6:7], 0, s[44:45]
	v_lshl_add_u64 v[6:7], v[6:7], 0, v[2:3]
	s_or_b64 exec, exec, s[0:1]
	v_and_b32_e32 v13, 64, v221
	v_xor_b32_e32 v1, 32, v221
	v_add_u32_e32 v13, 64, v13
	v_cmp_lt_i32_e32 vcc, v1, v13
	v_mov_b32_e32 v4, 0
	s_nop 0
	v_cndmask_b32_e32 v1, v221, v1, vcc
	v_lshlrev_b32_e32 v1, 2, v1
	ds_bpermute_b32 v1, v1, v240
	s_waitcnt lgkmcnt(0)
	v_add_f32_e32 v1, v240, v1
	v_cmp_lt_f32_e32 vcc, 0, v1
	s_and_saveexec_b64 s[0:1], vcc
	s_waitcnt vmcnt(0)
	v_div_scale_f32 v4, s[2:3], v1, v1, v16
	v_rcp_f32_e32 v5, v4
	v_div_scale_f32 v12, vcc, v16, v1, v16
	v_fma_f32 v13, -v4, v5, 1.0
	v_fmac_f32_e32 v5, v13, v5
	v_mul_f32_e32 v13, v12, v5
	v_fma_f32 v14, -v4, v13, v12
	v_fmac_f32_e32 v13, v14, v5
	v_fma_f32 v4, -v4, v13, v12
	v_div_fmas_f32 v4, v4, v5, v13
	v_div_fixup_f32 v4, v4, v1, v16
	s_or_b64 exec, exec, s[0:1]
	s_and_saveexec_b64 s[0:1], s[22:23]
	v_readlane_b32 s79, v252, 40
	s_mov_b32 s33, 0x58000
	s_movk_i32 s40, 0x5800
	s_mov_b32 s41, 0x16000
	s_mov_b32 s42, 0x2c000
	s_mov_b32 s43, 0x42000
	s_mov_b32 s46, 0x6e000
	s_mov_b32 s47, 0x84000
	s_mov_b32 s50, 0x9a000
	s_mov_b32 s51, 0xb0000
	s_mov_b32 s52, 0xc6000
	s_mov_b32 s53, 0xdc000
	s_mov_b32 s56, 0xf2000
	s_mov_b32 s57, 0x108000
	v_readlane_b32 s90, v252, 43
	v_readlane_b32 s81, v252, 39
	s_cbranch_execz .LBB0_2145
; __device__ __forceinline__ unsigned pk2(float lo, float hi) { const bfx2 b = __builtin_convertvector((f32x2){lo, hi}, bfx2); return __builtin_bit_cast(unsigned, b); }
; __device__ __forceinline__ float bflo(unsigned w) { return __uint_as_float(w << 16); }
; __device__ __forceinline__ float bfhi(unsigned w) { return __uint_as_float(w & 0xffff0000u); }
; #define PKP(var) unsigned char* var; { int l_ = threadIdx.x; asm volatile("" : "+v"(l_)); var = ws + WS_PARK + (size_t)(item8 + (l_ >> 6)) * 8192 + (l_ & 63) * 16; }
; __device__ __forceinline__ void attn_item(const P& p, Frame& F, const bool is_s, const int b, const int g, const int c) {
;     ...
;     { const float lt = l + __shfl_xor(l, 32); const float sc = lt > 0.f ? NGt[(size_t)mrow * 32 + 2 * 8 + h] / lt : 0.f;
;       if (qvalid) { PKP(PK);
; #pragma unroll
;           for (int dt = 0; dt < 4; ++dt)
; #pragma unroll
;               for (int hf = 0; hf < 2; ++hf) { const u32x4 o4 = *(const u32x4*)(PK + (2 * dt + hf) * 1024);
; #pragma unroll
;                   for (int rr = 0; rr < 2; ++rr) { const int r4 = 2 * hf + rr; const int d0 = 32 * dt + 8 * r4 + 4 * half; const u32x2 o = rr ? (u32x2){o4.z, o4.w} : (u32x2){o4.x, o4.y};
;                       u32x2 w; w.x = pk2(bflo(o.x) + ot[dt][4 * r4 + 0] * sc, bfhi(o.x) + ot[dt][4 * r4 + 1] * sc); w.y = pk2(bflo(o.y) + ot[dt][4 * r4 + 2] * sc, bfhi(o.y) + ot[dt][4 * r4 + 3] * sc);
;                       *(u32x2*)(YN + (size_t)mrow * 1024 + h * 128 + d0) = w; } } } }
	s_waitcnt vmcnt(0)
	v_lshlrev_b32_e32 v12, 16, v114
	v_and_b32_e32 v13, 0xffff0000, v114
	v_fma_f32 v12, v66, v4, v12
	v_fma_f32 v13, v67, v4, v13
	s_nop 0
	v_cvt_pk_bf16_f32 v114, v12, v13
	v_lshlrev_b32_e32 v14, 16, v115
	v_and_b32_e32 v15, 0xffff0000, v115
	v_fma_f32 v14, v68, v4, v14
	v_fma_f32 v15, v69, v4, v15
	s_nop 0
	v_cvt_pk_bf16_f32 v115, v14, v15
	v_lshlrev_b32_e32 v16, 16, v116
	v_and_b32_e32 v17, 0xffff0000, v116
	v_fma_f32 v16, v70, v4, v16
	v_fma_f32 v17, v71, v4, v17
	s_nop 0
	v_cvt_pk_bf16_f32 v116, v16, v17
	v_lshlrev_b32_e32 v12, 16, v117
	v_and_b32_e32 v13, 0xffff0000, v117
	v_fma_f32 v12, v72, v4, v12
	v_fma_f32 v13, v73, v4, v13
	s_nop 0
	v_cvt_pk_bf16_f32 v117, v12, v13
	s_nop 1
	v_permlane32_swap_b32_e32 v114, v116
	v_permlane32_swap_b32_e32 v115, v117
	global_store_dwordx4 v[6:7], v[114:117], off
	v_lshlrev_b32_e32 v14, 16, v118
	v_and_b32_e32 v15, 0xffff0000, v118
	v_fma_f32 v14, v74, v4, v14
	v_fma_f32 v15, v75, v4, v15
	s_nop 0
	v_cvt_pk_bf16_f32 v118, v14, v15
	v_lshlrev_b32_e32 v16, 16, v119
	v_and_b32_e32 v17, 0xffff0000, v119
	v_fma_f32 v16, v76, v4, v16
	v_fma_f32 v17, v77, v4, v17
	s_nop 0
	v_cvt_pk_bf16_f32 v119, v16, v17
	v_lshlrev_b32_e32 v12, 16, v120
	v_and_b32_e32 v13, 0xffff0000, v120
	v_fma_f32 v12, v78, v4, v12
	v_fma_f32 v13, v79, v4, v13
	s_nop 0
	v_cvt_pk_bf16_f32 v120, v12, v13
	v_lshlrev_b32_e32 v14, 16, v121
	v_and_b32_e32 v15, 0xffff0000, v121
	v_fma_f32 v14, v80, v4, v14
	v_fma_f32 v15, v81, v4, v15
	s_nop 0
	v_cvt_pk_bf16_f32 v121, v14, v15
	s_nop 1
	v_permlane32_swap_b32_e32 v118, v120
	v_permlane32_swap_b32_e32 v119, v121
	global_store_dwordx4 v[6:7], v[118:121], off offset:32
	v_lshlrev_b32_e32 v16, 16, v122
	v_and_b32_e32 v17, 0xffff0000, v122
	v_fma_f32 v16, v50, v4, v16
	v_fma_f32 v17, v51, v4, v17
	s_nop 0
	v_cvt_pk_bf16_f32 v122, v16, v17
	v_lshlrev_b32_e32 v12, 16, v123
	v_and_b32_e32 v13, 0xffff0000, v123
	v_fma_f32 v12, v52, v4, v12
	v_fma_f32 v13, v53, v4, v13
	s_nop 0
	v_cvt_pk_bf16_f32 v123, v12, v13
	v_lshlrev_b32_e32 v14, 16, v124
	v_and_b32_e32 v15, 0xffff0000, v124
	v_fma_f32 v14, v54, v4, v14
	v_fma_f32 v15, v55, v4, v15
	s_nop 0
	v_cvt_pk_bf16_f32 v124, v14, v15
	v_lshlrev_b32_e32 v16, 16, v125
	v_and_b32_e32 v17, 0xffff0000, v125
	v_fma_f32 v16, v56, v4, v16
	v_fma_f32 v17, v57, v4, v17
	s_nop 0
	v_cvt_pk_bf16_f32 v125, v16, v17
	s_nop 1
	v_permlane32_swap_b32_e32 v122, v124
	v_permlane32_swap_b32_e32 v123, v125
	global_store_dwordx4 v[6:7], v[122:125], off offset:64
	v_lshlrev_b32_e32 v12, 16, v126
	v_and_b32_e32 v13, 0xffff0000, v126
	v_fma_f32 v12, v58, v4, v12
	v_fma_f32 v13, v59, v4, v13
	s_nop 0
	v_cvt_pk_bf16_f32 v126, v12, v13
	v_lshlrev_b32_e32 v14, 16, v127
	v_and_b32_e32 v15, 0xffff0000, v127
	v_fma_f32 v14, v60, v4, v14
	v_fma_f32 v15, v61, v4, v15
	s_nop 0
	v_cvt_pk_bf16_f32 v127, v14, v15
	v_lshlrev_b32_e32 v16, 16, v128
	v_and_b32_e32 v17, 0xffff0000, v128
	v_fma_f32 v16, v62, v4, v16
	v_fma_f32 v17, v63, v4, v17
	s_nop 0
	v_cvt_pk_bf16_f32 v128, v16, v17
	v_lshlrev_b32_e32 v12, 16, v129
	v_and_b32_e32 v13, 0xffff0000, v129
	v_fma_f32 v12, v64, v4, v12
	v_fma_f32 v13, v65, v4, v13
	s_nop 0
	v_cvt_pk_bf16_f32 v129, v12, v13
	s_nop 1
	v_permlane32_swap_b32_e32 v126, v128
	v_permlane32_swap_b32_e32 v127, v129
	global_store_dwordx4 v[6:7], v[126:129], off offset:96
	v_lshlrev_b32_e32 v14, 16, v130
	v_and_b32_e32 v15, 0xffff0000, v130
	v_fma_f32 v14, v34, v4, v14
	v_fma_f32 v15, v35, v4, v15
	s_nop 0
	v_cvt_pk_bf16_f32 v130, v14, v15
	v_lshlrev_b32_e32 v16, 16, v131
	v_and_b32_e32 v17, 0xffff0000, v131
	v_fma_f32 v16, v36, v4, v16
	v_fma_f32 v17, v37, v4, v17
	s_nop 0
	v_cvt_pk_bf16_f32 v131, v16, v17
	v_lshlrev_b32_e32 v12, 16, v132
	v_and_b32_e32 v13, 0xffff0000, v132
	v_fma_f32 v12, v38, v4, v12
	v_fma_f32 v13, v39, v4, v13
	s_nop 0
	v_cvt_pk_bf16_f32 v132, v12, v13
	v_lshlrev_b32_e32 v14, 16, v133
	v_and_b32_e32 v15, 0xffff0000, v133
	v_fma_f32 v14, v40, v4, v14
	v_fma_f32 v15, v41, v4, v15
	s_nop 0
	v_cvt_pk_bf16_f32 v133, v14, v15
	s_nop 1
	v_permlane32_swap_b32_e32 v130, v132
	v_permlane32_swap_b32_e32 v131, v133
	global_store_dwordx4 v[6:7], v[130:133], off offset:128
	v_lshlrev_b32_e32 v16, 16, v134
	v_and_b32_e32 v17, 0xffff0000, v134
	v_fma_f32 v16, v42, v4, v16
	v_fma_f32 v17, v43, v4, v17
	s_nop 0
	v_cvt_pk_bf16_f32 v134, v16, v17
	v_lshlrev_b32_e32 v12, 16, v135
	v_and_b32_e32 v13, 0xffff0000, v135
	v_fma_f32 v12, v44, v4, v12
	v_fma_f32 v13, v45, v4, v13
	s_nop 0
	v_cvt_pk_bf16_f32 v135, v12, v13
	v_lshlrev_b32_e32 v14, 16, v136
	v_and_b32_e32 v15, 0xffff0000, v136
	v_fma_f32 v14, v46, v4, v14
	v_fma_f32 v15, v47, v4, v15
	s_nop 0
	v_cvt_pk_bf16_f32 v136, v14, v15
	v_lshlrev_b32_e32 v16, 16, v137
	v_and_b32_e32 v17, 0xffff0000, v137
	v_fma_f32 v16, v48, v4, v16
	v_fma_f32 v17, v49, v4, v17
	s_nop 0
	v_cvt_pk_bf16_f32 v137, v16, v17
	s_nop 1
	v_permlane32_swap_b32_e32 v134, v136
	v_permlane32_swap_b32_e32 v135, v137
	global_store_dwordx4 v[6:7], v[134:137], off offset:160
	v_lshlrev_b32_e32 v12, 16, v138
	v_and_b32_e32 v13, 0xffff0000, v138
	v_fma_f32 v12, v18, v4, v12
	v_fma_f32 v13, v19, v4, v13
	s_nop 0
	v_cvt_pk_bf16_f32 v138, v12, v13
	v_lshlrev_b32_e32 v14, 16, v139
	v_and_b32_e32 v15, 0xffff0000, v139
	v_fma_f32 v14, v20, v4, v14
	v_fma_f32 v15, v21, v4, v15
	s_nop 0
	v_cvt_pk_bf16_f32 v139, v14, v15
	v_lshlrev_b32_e32 v16, 16, v140
	v_and_b32_e32 v17, 0xffff0000, v140
	v_fma_f32 v16, v22, v4, v16
	v_fma_f32 v17, v23, v4, v17
	s_nop 0
	v_cvt_pk_bf16_f32 v140, v16, v17
	v_lshlrev_b32_e32 v12, 16, v141
	v_and_b32_e32 v13, 0xffff0000, v141
	v_fma_f32 v12, v24, v4, v12
	v_fma_f32 v13, v25, v4, v13
	s_nop 0
	v_cvt_pk_bf16_f32 v141, v12, v13
	s_nop 1
	v_permlane32_swap_b32_e32 v138, v140
	v_permlane32_swap_b32_e32 v139, v141
	global_store_dwordx4 v[6:7], v[138:141], off offset:192
	v_lshlrev_b32_e32 v14, 16, v142
	v_and_b32_e32 v15, 0xffff0000, v142
	v_fma_f32 v14, v26, v4, v14
	v_fma_f32 v15, v27, v4, v15
	s_nop 0
	v_cvt_pk_bf16_f32 v142, v14, v15
	v_lshlrev_b32_e32 v16, 16, v143
	v_and_b32_e32 v17, 0xffff0000, v143
	v_fma_f32 v16, v28, v4, v16
	v_fma_f32 v17, v29, v4, v17
	s_nop 0
	v_cvt_pk_bf16_f32 v143, v16, v17
	v_lshlrev_b32_e32 v12, 16, v144
	v_and_b32_e32 v13, 0xffff0000, v144
	v_fma_f32 v12, v30, v4, v12
	v_fma_f32 v13, v31, v4, v13
	s_nop 0
	v_cvt_pk_bf16_f32 v144, v12, v13
	v_lshlrev_b32_e32 v14, 16, v145
	v_and_b32_e32 v15, 0xffff0000, v145
	v_fma_f32 v14, v32, v4, v14
	v_fma_f32 v15, v33, v4, v15
	s_nop 0
	v_cvt_pk_bf16_f32 v145, v14, v15
	s_nop 1
	v_permlane32_swap_b32_e32 v142, v144
	v_permlane32_swap_b32_e32 v143, v145
	global_store_dwordx4 v[6:7], v[142:145], off offset:224
